# hold raised priority from QK through PV (two fewer priority switches per tile)
# baseline (speedup 1.0000x reference)
; __device__ __forceinline__ void attn_tile(const u16* sb, const bf16x8 (&qa)[6], f32x16& o0, f32x16& o1, f32x16& lacc,
;                                           float& m, bool& mz, int r, int h, bool first) {
;     ...
;   float mxa = max3f(s0[0], s0[1], s0[2]), mxb = max3f(s0[3], s0[4], s0[5]);
;   float mxc = max3f(s0[6], s0[7], s0[8]), mxd = max3f(s0[9], s0[10], s0[11]);
;   mxa = max3f(mxa, s0[12], s0[13]); mxb = max3f(mxb, s0[14], s0[15]);
;   mxc = max3f(mxc, s1[0], s1[1]); mxd = max3f(mxd, s1[2], s1[3]);
;   mxa = max3f(mxa, s1[4], s1[5]); mxb = max3f(mxb, s1[6], s1[7]);
;   mxc = max3f(mxc, s1[8], s1[9]); mxd = max3f(mxd, s1[10], s1[11]);
;   mxa = max3f(mxa, s1[12], s1[13]); mxb = max3f(mxb, s1[14], s1[15]);
;   const float lm = max3f(mxa, mxb, fmaxf(mxc, mxd));
;   bool slow;
;   if (first) {
;     const float mx = fmaxf(lm, __shfl_xor(lm, 32));
;     slow = __any(mx > 30.f || mx < -30.f);
;   } else {
;     slow = __any(lm > 30.f);
;   }
;   if (slow) {
;     const float mx = fmaxf(lm, __shfl_xor(lm, 32));
;     const float d = first ? mx : fmaxf(mx, 0.f);
;     const float alpha = first ? 1.f : __builtin_amdgcn_exp2f(-d);
;     m += d;
;     mz = false;
; #pragma unroll
;     for (int i = 0; i < 16; ++i) { s0[i] -= d; s1[i] -= d; o0[i] *= alpha; o1[i] *= alpha; }
;     lacc[0] *= alpha;
;   }
;   float pa = 0.f, pb = 0.f, pc = 0.f, pd = 0.f;
; #pragma unroll
;   for (int i = 0; i < 16; ++i) {
;     s0[i] = __builtin_amdgcn_exp2f(s0[i]); s1[i] = __builtin_amdgcn_exp2f(s1[i]);
;     if ((i & 3) == 0) pa += s0[i] + s1[i];
;     else if ((i & 3) == 1) pb += s0[i] + s1[i];
;     else if ((i & 3) == 2) pc += s0[i] + s1[i];
;     else pd += s0[i] + s1[i];
;   }
;   lacc[0] += (pa + pb) + (pc + pd);
;   const u16* vp = sb + 64 * KLD + r * VLD + 8 * h;
;   __builtin_amdgcn_s_setprio(1);
; #pragma unroll
;   for (int kb = 0; kb < 2; ++kb) {
; #pragma unroll
;     for (int s = 0; s < 2; ++s) {
;       const bf16x8 pf = pack_p(kb == 0 ? s0 : s1, 8 * s);
;       const int koff = kb * 32 + 16 * s;
;       const bf16x8 v0 = *(const bf16x8*)(vp + koff);
;       const bf16x8 v1 = *(const bf16x8*)(vp + 32 * VLD + koff);
;       o0 = mfma32(v0, pf, o0);
;       o1 = mfma32(v1, pf, o1);
;     }
;   }
;   __builtin_amdgcn_s_setprio(0);
.Lqkd_e:
	ds_read_b128 v[214:217], v163 offset:13312
	ds_read_b128 v[218:221], v163 offset:17920
	ds_read_b128 v[222:225], v163 offset:13344
	ds_read_b128 v[226:229], v163 offset:17952
	ds_read_b128 v[230:233], v163 offset:13376
	ds_read_b128 v[234:237], v163 offset:17984
	ds_read_b128 v[238:241], v163 offset:13408
	ds_read_b128 v[242:245], v163 offset:18016
	s_nop 1
	v_max3_f32 v142, v50, v51, v52
	v_max3_f32 v144, v56, v57, v58
	v_max3_f32 v145, v59, v60, v61
	v_max3_f32 v143, v53, v54, v55
	v_max3_f32 v142, v142, v62, v63
	v_max3_f32 v144, v144, v34, v35
	v_max3_f32 v145, v145, v36, v37
	v_max3_f32 v143, v143, v64, v65
	v_max3_f32 v142, v142, v38, v39
	v_max3_f32 v144, v144, v42, v43
	v_max3_f32 v145, v145, v44, v45
	v_max3_f32 v143, v143, v40, v41
	v_max3_f32 v142, v142, v46, v47
	v_max_f32_e32 v145, v145, v145
	v_max_f32_e32 v144, v144, v144
	v_max3_f32 v143, v143, v48, v49
	v_max_f32_e32 v144, v144, v145
	v_max3_f32 v142, v142, v143, v144
	v_cmp_lt_f32_e32 vcc, s5, v142
	s_cbranch_vccz .LBB0_464
	ds_bpermute_b32 v143, v161, v142
	s_andn2_b64 s[48:49], s[48:49], exec
	s_waitcnt lgkmcnt(0)
	v_max3_f32 v142, v142, v143, 0
	v_exp_f32_e64 v144, -v142
	v_add_f32_e32 v162, v162, v142
	v_pk_add_f32 v[50:51], v[50:51], v[142:143] op_sel_hi:[1,0] neg_lo:[0,1] neg_hi:[0,1]
	v_pk_add_f32 v[34:35], v[34:35], v[142:143] op_sel_hi:[1,0] neg_lo:[0,1] neg_hi:[0,1]
	v_pk_add_f32 v[52:53], v[52:53], v[142:143] op_sel_hi:[1,0] neg_lo:[0,1] neg_hi:[0,1]
	v_pk_add_f32 v[36:37], v[36:37], v[142:143] op_sel_hi:[1,0] neg_lo:[0,1] neg_hi:[0,1]
	v_pk_add_f32 v[54:55], v[54:55], v[142:143] op_sel_hi:[1,0] neg_lo:[0,1] neg_hi:[0,1]
	v_pk_add_f32 v[38:39], v[38:39], v[142:143] op_sel_hi:[1,0] neg_lo:[0,1] neg_hi:[0,1]
	v_pk_add_f32 v[56:57], v[56:57], v[142:143] op_sel_hi:[1,0] neg_lo:[0,1] neg_hi:[0,1]
	v_pk_add_f32 v[40:41], v[40:41], v[142:143] op_sel_hi:[1,0] neg_lo:[0,1] neg_hi:[0,1]
	v_pk_add_f32 v[58:59], v[58:59], v[142:143] op_sel_hi:[1,0] neg_lo:[0,1] neg_hi:[0,1]
	v_pk_add_f32 v[42:43], v[42:43], v[142:143] op_sel_hi:[1,0] neg_lo:[0,1] neg_hi:[0,1]
	v_pk_add_f32 v[60:61], v[60:61], v[142:143] op_sel_hi:[1,0] neg_lo:[0,1] neg_hi:[0,1]
	v_pk_add_f32 v[44:45], v[44:45], v[142:143] op_sel_hi:[1,0] neg_lo:[0,1] neg_hi:[0,1]
	v_pk_add_f32 v[62:63], v[62:63], v[142:143] op_sel_hi:[1,0] neg_lo:[0,1] neg_hi:[0,1]
	v_pk_add_f32 v[46:47], v[46:47], v[142:143] op_sel_hi:[1,0] neg_lo:[0,1] neg_hi:[0,1]
	v_pk_add_f32 v[64:65], v[64:65], v[142:143] op_sel_hi:[1,0] neg_lo:[0,1] neg_hi:[0,1]
	v_pk_add_f32 v[48:49], v[48:49], v[142:143] op_sel_hi:[1,0] neg_lo:[0,1] neg_hi:[0,1]
	v_pk_mul_f32 v[32:33], v[32:33], v[144:145] op_sel_hi:[1,0]
	v_pk_mul_f32 v[30:31], v[30:31], v[144:145] op_sel_hi:[1,0]
	v_pk_mul_f32 v[28:29], v[28:29], v[144:145] op_sel_hi:[1,0]
	v_pk_mul_f32 v[26:27], v[26:27], v[144:145] op_sel_hi:[1,0]
	v_pk_mul_f32 v[24:25], v[24:25], v[144:145] op_sel_hi:[1,0]
	v_pk_mul_f32 v[22:23], v[22:23], v[144:145] op_sel_hi:[1,0]
	v_pk_mul_f32 v[20:21], v[20:21], v[144:145] op_sel_hi:[1,0]
	v_pk_mul_f32 v[18:19], v[18:19], v[144:145] op_sel_hi:[1,0]
	v_pk_mul_f32 v[16:17], v[16:17], v[144:145] op_sel_hi:[1,0]
	v_pk_mul_f32 v[14:15], v[14:15], v[144:145] op_sel_hi:[1,0]
	v_pk_mul_f32 v[12:13], v[12:13], v[144:145] op_sel_hi:[1,0]
	v_pk_mul_f32 v[10:11], v[10:11], v[144:145] op_sel_hi:[1,0]
	v_pk_mul_f32 v[8:9], v[8:9], v[144:145] op_sel_hi:[1,0]
	v_pk_mul_f32 v[6:7], v[6:7], v[144:145] op_sel_hi:[1,0]
	v_pk_mul_f32 v[4:5], v[4:5], v[144:145] op_sel_hi:[1,0]
	v_pk_mul_f32 v[2:3], v[2:3], v[144:145] op_sel_hi:[1,0]
	v_mul_f32_e32 v136, v136, v144
.LBB0_464:
	v_exp_f32_e32 v147, v53
	v_exp_f32_e32 v149, v37
	v_exp_f32_e32 v145, v57
	v_exp_f32_e32 v53, v41
	v_exp_f32_e32 v143, v61
	v_exp_f32_e32 v45, v45
	v_exp_f32_e32 v37, v65
	v_exp_f32_e32 v41, v49
	v_exp_f32_e32 v146, v34
	v_exp_f32_e32 v152, v35
	v_exp_f32_e32 v153, v36
	v_exp_f32_e32 v144, v38
	v_exp_f32_e32 v150, v39
	v_exp_f32_e32 v151, v40
	v_exp_f32_e32 v142, v42
	v_exp_f32_e32 v38, v43
	v_exp_f32_e32 v39, v44
	v_exp_f32_e32 v36, v46
	v_exp_f32_e32 v34, v47
	v_exp_f32_e32 v35, v48
	v_exp_f32_e32 v148, v50
	v_exp_f32_e32 v50, v51
	v_exp_f32_e32 v51, v52
	v_exp_f32_e32 v52, v54
	v_exp_f32_e32 v48, v55
	v_exp_f32_e32 v49, v56
	v_exp_f32_e32 v44, v58
	v_exp_f32_e32 v46, v59
	v_exp_f32_e32 v47, v60
	v_exp_f32_e32 v40, v62
	v_exp_f32_e32 v42, v63
	v_exp_f32_e32 v43, v64
	v_cvt_pk_bf16_f32 v58, v148, v50
	v_cvt_pk_bf16_f32 v59, v51, v147
	v_cvt_pk_bf16_f32 v60, v52, v48
	v_cvt_pk_bf16_f32 v61, v49, v145
	v_cvt_pk_bf16_f32 v246, v44, v46
	v_cvt_pk_bf16_f32 v247, v47, v143
	v_cvt_pk_bf16_f32 v248, v40, v42
	v_cvt_pk_bf16_f32 v249, v43, v37
	s_waitcnt lgkmcnt(0)
	v_mfma_f32_32x32x16_bf16 v[18:33], v[214:217], v[58:61], v[18:33]
	v_mfma_f32_32x32x16_bf16 v[2:17], v[218:221], v[58:61], v[2:17]
	v_cvt_pk_bf16_f32 v58, v146, v152
	v_cvt_pk_bf16_f32 v59, v153, v149
	v_cvt_pk_bf16_f32 v60, v144, v150
	v_cvt_pk_bf16_f32 v61, v151, v53
	v_mfma_f32_32x32x16_bf16 v[18:33], v[222:225], v[246:249], v[18:33]
	v_mfma_f32_32x32x16_bf16 v[2:17], v[226:229], v[246:249], v[2:17]
	v_cvt_pk_bf16_f32 v246, v142, v38
	v_cvt_pk_bf16_f32 v247, v39, v45
	v_cvt_pk_bf16_f32 v248, v36, v34
	v_cvt_pk_bf16_f32 v249, v35, v41
	v_mfma_f32_32x32x16_bf16 v[18:33], v[230:233], v[58:61], v[18:33]
	v_mfma_f32_32x32x16_bf16 v[2:17], v[234:237], v[58:61], v[2:17]
	v_mfma_f32_32x32x16_bf16 v[18:33], v[238:241], v[246:249], v[18:33]
	v_mfma_f32_32x32x16_bf16 v[2:17], v[242:245], v[246:249], v[2:17]
	s_setprio 0
	s_cmp_lg_u64 s[0:1], 0
	s_cbranch_scc0 .Lattn_w0
	s_waitcnt vmcnt(5)
	s_branch .Lattn_w1

; __device__ __forceinline__ void attn_tile(const u16* sb, const bf16x8 (&qa)[6], f32x16& o0, f32x16& o1, f32x16& lacc,
;                                           float& m, bool& mz, int r, int h, bool first) {
;     ...
;   float mxa = max3f(s0[0], s0[1], s0[2]), mxb = max3f(s0[3], s0[4], s0[5]);
;   float mxc = max3f(s0[6], s0[7], s0[8]), mxd = max3f(s0[9], s0[10], s0[11]);
;   mxa = max3f(mxa, s0[12], s0[13]); mxb = max3f(mxb, s0[14], s0[15]);
;   mxc = max3f(mxc, s1[0], s1[1]); mxd = max3f(mxd, s1[2], s1[3]);
;   mxa = max3f(mxa, s1[4], s1[5]); mxb = max3f(mxb, s1[6], s1[7]);
;   mxc = max3f(mxc, s1[8], s1[9]); mxd = max3f(mxd, s1[10], s1[11]);
;   mxa = max3f(mxa, s1[12], s1[13]); mxb = max3f(mxb, s1[14], s1[15]);
;   const float lm = max3f(mxa, mxb, fmaxf(mxc, mxd));
;   bool slow;
;   if (first) {
;     const float mx = fmaxf(lm, __shfl_xor(lm, 32));
;     slow = __any(mx > 30.f || mx < -30.f);
;   } else {
;     slow = __any(lm > 30.f);
;   }
;   if (slow) {
;     const float mx = fmaxf(lm, __shfl_xor(lm, 32));
;     const float d = first ? mx : fmaxf(mx, 0.f);
;     const float alpha = first ? 1.f : __builtin_amdgcn_exp2f(-d);
;     m += d;
;     mz = false;
; #pragma unroll
;     for (int i = 0; i < 16; ++i) { s0[i] -= d; s1[i] -= d; o0[i] *= alpha; o1[i] *= alpha; }
;     lacc[0] *= alpha;
;   }
.Lqkd_o:
	ds_read_b128 v[214:217], v163 offset:35840
	ds_read_b128 v[218:221], v163 offset:40448
	ds_read_b128 v[222:225], v163 offset:35872
	ds_read_b128 v[226:229], v163 offset:40480
	ds_read_b128 v[230:233], v163 offset:35904
	ds_read_b128 v[234:237], v163 offset:40512
	ds_read_b128 v[238:241], v163 offset:35936
	ds_read_b128 v[242:245], v163 offset:40544
	s_nop 1
	v_max3_f32 v138, v50, v51, v52
	v_max3_f32 v140, v56, v57, v58
	v_max3_f32 v141, v59, v60, v61
	v_max3_f32 v139, v53, v54, v55
	v_max3_f32 v138, v138, v62, v63
	v_max3_f32 v140, v140, v34, v35
	v_max3_f32 v141, v141, v36, v37
	v_max3_f32 v139, v139, v64, v65
	v_max3_f32 v138, v138, v38, v39
	v_max3_f32 v140, v140, v42, v43
	v_max3_f32 v141, v141, v44, v45
	v_max3_f32 v139, v139, v40, v41
	v_max3_f32 v138, v138, v46, v47
	v_max_f32_e32 v141, v141, v141
	v_max_f32_e32 v140, v140, v140
	v_max3_f32 v139, v139, v48, v49
	v_max_f32_e32 v140, v140, v141
	v_max3_f32 v138, v138, v139, v140
	v_cmp_lt_f32_e32 vcc, s5, v138
	s_cbranch_vccz .LBB0_473
	ds_bpermute_b32 v139, v161, v138
	s_andn2_b64 s[50:51], s[48:49], exec
	s_waitcnt lgkmcnt(0)
	v_max3_f32 v138, v138, v139, 0
	v_exp_f32_e64 v140, -v138
	v_add_f32_e32 v162, v162, v138
	v_pk_add_f32 v[50:51], v[50:51], v[138:139] op_sel_hi:[1,0] neg_lo:[0,1] neg_hi:[0,1]
	v_pk_add_f32 v[34:35], v[34:35], v[138:139] op_sel_hi:[1,0] neg_lo:[0,1] neg_hi:[0,1]
	v_pk_add_f32 v[52:53], v[52:53], v[138:139] op_sel_hi:[1,0] neg_lo:[0,1] neg_hi:[0,1]
	v_pk_add_f32 v[36:37], v[36:37], v[138:139] op_sel_hi:[1,0] neg_lo:[0,1] neg_hi:[0,1]
	v_pk_add_f32 v[54:55], v[54:55], v[138:139] op_sel_hi:[1,0] neg_lo:[0,1] neg_hi:[0,1]
	v_pk_add_f32 v[38:39], v[38:39], v[138:139] op_sel_hi:[1,0] neg_lo:[0,1] neg_hi:[0,1]
	v_pk_add_f32 v[56:57], v[56:57], v[138:139] op_sel_hi:[1,0] neg_lo:[0,1] neg_hi:[0,1]
	v_pk_add_f32 v[40:41], v[40:41], v[138:139] op_sel_hi:[1,0] neg_lo:[0,1] neg_hi:[0,1]
	v_pk_add_f32 v[58:59], v[58:59], v[138:139] op_sel_hi:[1,0] neg_lo:[0,1] neg_hi:[0,1]
	v_pk_add_f32 v[42:43], v[42:43], v[138:139] op_sel_hi:[1,0] neg_lo:[0,1] neg_hi:[0,1]
	v_pk_add_f32 v[60:61], v[60:61], v[138:139] op_sel_hi:[1,0] neg_lo:[0,1] neg_hi:[0,1]
	v_pk_add_f32 v[44:45], v[44:45], v[138:139] op_sel_hi:[1,0] neg_lo:[0,1] neg_hi:[0,1]
	v_pk_add_f32 v[62:63], v[62:63], v[138:139] op_sel_hi:[1,0] neg_lo:[0,1] neg_hi:[0,1]
	v_pk_add_f32 v[46:47], v[46:47], v[138:139] op_sel_hi:[1,0] neg_lo:[0,1] neg_hi:[0,1]
	v_pk_add_f32 v[64:65], v[64:65], v[138:139] op_sel_hi:[1,0] neg_lo:[0,1] neg_hi:[0,1]
	v_pk_add_f32 v[48:49], v[48:49], v[138:139] op_sel_hi:[1,0] neg_lo:[0,1] neg_hi:[0,1]
	v_pk_mul_f32 v[32:33], v[32:33], v[140:141] op_sel_hi:[1,0]
	v_pk_mul_f32 v[30:31], v[30:31], v[140:141] op_sel_hi:[1,0]
	v_pk_mul_f32 v[28:29], v[28:29], v[140:141] op_sel_hi:[1,0]
	v_pk_mul_f32 v[26:27], v[26:27], v[140:141] op_sel_hi:[1,0]
	v_pk_mul_f32 v[24:25], v[24:25], v[140:141] op_sel_hi:[1,0]
	v_pk_mul_f32 v[22:23], v[22:23], v[140:141] op_sel_hi:[1,0]
	v_pk_mul_f32 v[20:21], v[20:21], v[140:141] op_sel_hi:[1,0]
	v_pk_mul_f32 v[18:19], v[18:19], v[140:141] op_sel_hi:[1,0]
	v_pk_mul_f32 v[16:17], v[16:17], v[140:141] op_sel_hi:[1,0]
	v_pk_mul_f32 v[14:15], v[14:15], v[140:141] op_sel_hi:[1,0]
	v_pk_mul_f32 v[12:13], v[12:13], v[140:141] op_sel_hi:[1,0]
	v_pk_mul_f32 v[10:11], v[10:11], v[140:141] op_sel_hi:[1,0]
	v_pk_mul_f32 v[8:9], v[8:9], v[140:141] op_sel_hi:[1,0]
	v_pk_mul_f32 v[6:7], v[6:7], v[140:141] op_sel_hi:[1,0]
	v_pk_mul_f32 v[4:5], v[4:5], v[140:141] op_sel_hi:[1,0]
	v_pk_mul_f32 v[2:3], v[2:3], v[140:141] op_sel_hi:[1,0]
	v_mul_f32_e32 v136, v136, v140
	s_branch .LBB0_474

; __device__ __forceinline__ void attn_tile(const u16* sb, const bf16x8 (&qa)[6], f32x16& o0, f32x16& o1, f32x16& lacc,
;                                           float& m, bool& mz, int r, int h, bool first) {
;     ...
;   float pa = 0.f, pb = 0.f, pc = 0.f, pd = 0.f;
; #pragma unroll
;   for (int i = 0; i < 16; ++i) {
;     s0[i] = __builtin_amdgcn_exp2f(s0[i]); s1[i] = __builtin_amdgcn_exp2f(s1[i]);
;     if ((i & 3) == 0) pa += s0[i] + s1[i];
;     else if ((i & 3) == 1) pb += s0[i] + s1[i];
;     else if ((i & 3) == 2) pc += s0[i] + s1[i];
;     else pd += s0[i] + s1[i];
;   }
;   lacc[0] += (pa + pb) + (pc + pd);
;   const u16* vp = sb + 64 * KLD + r * VLD + 8 * h;
;   __builtin_amdgcn_s_setprio(1);
; #pragma unroll
;   for (int kb = 0; kb < 2; ++kb) {
; #pragma unroll
;     for (int s = 0; s < 2; ++s) {
;       const bf16x8 pf = pack_p(kb == 0 ? s0 : s1, 8 * s);
;       const int koff = kb * 32 + 16 * s;
;       const bf16x8 v0 = *(const bf16x8*)(vp + koff);
;       const bf16x8 v1 = *(const bf16x8*)(vp + 32 * VLD + koff);
;       o0 = mfma32(v0, pf, o0);
;       o1 = mfma32(v1, pf, o1);
;     }
;   }
;   __builtin_amdgcn_s_setprio(0);
.LBB0_474:
	v_exp_f32_e32 v148, v35
	v_exp_f32_e32 v149, v36
	v_exp_f32_e32 v142, v38
	v_exp_f32_e32 v150, v39
	v_exp_f32_e32 v38, v51
	v_exp_f32_e32 v39, v52
	v_exp_f32_e32 v139, v53
	v_exp_f32_e32 v53, v41
	v_exp_f32_e32 v151, v40
	v_exp_f32_e32 v40, v55
	v_exp_f32_e32 v41, v56
	v_exp_f32_e32 v144, v42
	v_exp_f32_e32 v42, v43
	v_exp_f32_e32 v43, v44
	v_exp_f32_e32 v140, v50
	v_exp_f32_e32 v50, v59
	v_exp_f32_e32 v51, v60
	v_exp_f32_e32 v146, v46
	v_exp_f32_e32 v46, v47
	v_exp_f32_e32 v47, v48
	v_exp_f32_e32 v52, v54
	v_exp_f32_e32 v54, v63
	v_exp_f32_e32 v55, v64
	v_exp_f32_e32 v141, v37
	v_exp_f32_e32 v138, v34
	v_pk_add_f32 v[34:35], v[38:39], v[148:149]
	v_exp_f32_e32 v143, v57
	v_pk_add_f32 v[36:37], v[40:41], v[150:151]
	v_exp_f32_e32 v145, v61
	v_exp_f32_e32 v45, v45
	v_exp_f32_e32 v44, v58
	v_pk_add_f32 v[34:35], v[36:37], v[34:35]
	v_pk_add_f32 v[36:37], v[50:51], v[42:43]
	v_exp_f32_e32 v147, v65
	v_exp_f32_e32 v49, v49
	v_exp_f32_e32 v48, v62
	v_pk_add_f32 v[34:35], v[36:37], v[34:35]
	v_pk_add_f32 v[36:37], v[54:55], v[46:47]
	v_pk_add_f32 v[56:57], v[52:53], v[142:143]
	v_pk_add_f32 v[34:35], v[36:37], v[34:35]
	v_pk_add_f32 v[36:37], v[140:141], v[138:139]
	s_nop 0
	s_nop 0
	v_pk_add_f32 v[36:37], v[56:57], v[36:37]
	v_pk_add_f32 v[56:57], v[44:45], v[144:145]
	s_nop 0
	v_pk_add_f32 v[36:37], v[56:57], v[36:37]
	v_pk_add_f32 v[56:57], v[48:49], v[146:147]
	s_nop 0
	v_pk_add_f32 v[36:37], v[56:57], v[36:37]
	s_nop 0
	v_pk_add_f32 v[34:35], v[34:35], v[36:37]
	s_nop 0
	v_add_f32_e32 v34, v34, v35
	v_add_f32_e32 v136, v136, v34
	v_cvt_pk_bf16_f32 v38, v140, v38
	v_cvt_pk_bf16_f32 v39, v39, v139
	v_cvt_pk_bf16_f32 v40, v52, v40
	v_cvt_pk_bf16_f32 v41, v41, v143
	v_cvt_pk_bf16_f32 v246, v44, v50
	v_cvt_pk_bf16_f32 v247, v51, v145
	v_cvt_pk_bf16_f32 v248, v48, v54
	v_cvt_pk_bf16_f32 v249, v55, v147
	s_waitcnt lgkmcnt(0)
	v_mfma_f32_32x32x16_bf16 v[18:33], v[214:217], v[38:41], v[18:33]
	v_mfma_f32_32x32x16_bf16 v[2:17], v[218:221], v[38:41], v[2:17]
	v_cvt_pk_bf16_f32 v38, v138, v148
	v_cvt_pk_bf16_f32 v39, v149, v141
	v_cvt_pk_bf16_f32 v40, v142, v150
	v_cvt_pk_bf16_f32 v41, v151, v53
	v_mfma_f32_32x32x16_bf16 v[18:33], v[222:225], v[246:249], v[18:33]
	v_mfma_f32_32x32x16_bf16 v[2:17], v[226:229], v[246:249], v[2:17]
	v_cvt_pk_bf16_f32 v246, v144, v42
	v_cvt_pk_bf16_f32 v247, v43, v45
	v_cvt_pk_bf16_f32 v248, v146, v46
	v_cvt_pk_bf16_f32 v249, v47, v49
	v_mfma_f32_32x32x16_bf16 v[18:33], v[230:233], v[38:41], v[18:33]
	v_mfma_f32_32x32x16_bf16 v[2:17], v[234:237], v[38:41], v[2:17]
	v_mfma_f32_32x32x16_bf16 v[18:33], v[238:241], v[246:249], v[18:33]
	v_mfma_f32_32x32x16_bf16 v[2:17], v[242:245], v[246:249], v[2:17]
	s_setprio 0
	s_andn2_b64 s[48:49], s[48:49], exec
	s_and_b64 s[50:51], s[50:51], exec
	s_or_b64 s[48:49], s[48:49], s[50:51]
